# HGRN: prefetch addressing by running 64-bit pointers (one add per load) and chunk-0 loads issued up front; on top of GEMM late fragment reads, HGRN logf trim, attention rescale skip
# speedup vs baseline: 1.0428x; 1.0091x over previous
.LBB0_783:
	s_sub_i32 s24, s48, 64
	s_lshr_b32 s29, s24, 3
	s_and_b64 s[24:25], exec, s[0:1]
	s_movk_i32 s24, 0x400
	s_cselect_b32 s27, s24, 0x100
	s_cselect_b32 s24, s28, s29
	s_lshl_b32 s24, s24, 10
	s_addk_i32 s24, 0x2000
	s_lshl_b32 s25, s29, 8
	s_and_b64 s[0:1], exec, s[0:1]
	s_cselect_b32 s97, s24, s25
	s_lshr_b32 s30, s27, 5
	s_cmp_eq_u32 s2, 0
	s_cselect_b64 vcc, -1, 0
	s_and_b64 s[0:1], vcc, exec
	s_mov_b32 s0, 0xc4fd000
	s_cselect_b32 s0, s0, 0xe4fd000
	s_add_u32 s0, s94, s0
	s_addc_u32 s1, s95, 0
	s_lshl_b32 s24, s21, 9
	s_add_u32 s36, s0, s24
	s_addc_u32 s37, s1, 0
	s_lshl_b32 s0, s21, 8
	v_readlane_b32 s1, v234, 14
	s_add_u32 s28, s1, s0
	v_readlane_b32 s1, v234, 15
	v_writelane_b32 v232, s29, 57
	s_addc_u32 s29, s1, 0
	v_readlane_b32 s1, v234, 16
	s_add_u32 s0, s1, s0
	v_readlane_b32 s1, v234, 17
	s_addc_u32 s1, s1, 0
	s_lshl_b32 s25, s2, 25
	v_readlane_b32 s38, v235, 44
	s_add_u32 s25, s38, s25
	v_readlane_b32 s38, v235, 45
	s_addc_u32 s38, s38, 0
	s_add_u32 s40, s25, s24
	v_lshlrev_b32_e32 v32, 4, v81
	s_addc_u32 s41, s38, 0
	v_xad_u32 v34, v32, -1, s27
	s_and_b64 s[24:25], vcc, exec
	v_cndmask_b32_e32 v34, v34, v32, vcc
	s_cselect_b32 s24, 1, -1
	v_add_u32_e32 v34, s97, v34
	v_or_b32_e32 v42, v80, v133
	v_add_u32_e32 v36, s24, v34
	v_ashrrev_i32_e32 v35, 31, v34
	v_ashrrev_i32_e32 v43, 31, v42
	v_lshlrev_b64 v[34:35], 9, v[34:35]
	v_ashrrev_i32_e32 v37, 31, v36
	v_lshl_add_u64 v[34:35], v[34:35], 0, v[42:43]
	v_lshlrev_b64 v[36:37], 9, v[36:37]
	v_lshl_add_u64 v[38:39], v[34:35], 2, s[36:37]
	v_lshl_add_u64 v[36:37], v[36:37], 0, v[42:43]
	v_mov_b32_e32 v226, s24
	v_lshl_add_u64 v[222:223], v[34:35], 1, s[28:29]
	v_lshlrev_b32_e32 v226, 11, v226
	v_lshl_add_u64 v[224:225], v[34:35], 1, s[0:1]
	v_ashrrev_i32_e32 v227, 31, v226
	v_lshl_add_u64 v[220:221], v[34:35], 2, s[36:37]
	v_ashrrev_i32_e32 v228, 1, v226
	v_mov_b32_e32 v229, v227
	global_load_dword v236, v[220:221], off
	global_load_ushort v237, v[222:223], off
	global_load_ushort v238, v[224:225], off
	v_lshl_add_u64 v[220:221], v[220:221], 0, v[226:227]
	v_lshl_add_u64 v[222:223], v[222:223], 0, v[228:229]
	v_lshl_add_u64 v[224:225], v[224:225], 0, v[228:229]
	global_load_dword v239, v[220:221], off
	global_load_ushort v240, v[222:223], off
	global_load_ushort v241, v[224:225], off
	v_lshl_add_u64 v[220:221], v[220:221], 0, v[226:227]
	v_lshl_add_u64 v[222:223], v[222:223], 0, v[228:229]
	v_lshl_add_u64 v[224:225], v[224:225], 0, v[228:229]
	global_load_dword v242, v[220:221], off
	global_load_ushort v243, v[222:223], off
	global_load_ushort v244, v[224:225], off
	v_lshl_add_u64 v[220:221], v[220:221], 0, v[226:227]
	v_lshl_add_u64 v[222:223], v[222:223], 0, v[228:229]
	v_lshl_add_u64 v[224:225], v[224:225], 0, v[228:229]
	global_load_dword v245, v[220:221], off
	global_load_ushort v246, v[222:223], off
	global_load_ushort v247, v[224:225], off
	v_lshl_add_u64 v[220:221], v[220:221], 0, v[226:227]
	v_lshl_add_u64 v[222:223], v[222:223], 0, v[228:229]
	v_lshl_add_u64 v[224:225], v[224:225], 0, v[228:229]
	global_load_dword v248, v[220:221], off
	global_load_ushort v249, v[222:223], off
	global_load_ushort v250, v[224:225], off
	v_lshl_add_u64 v[220:221], v[220:221], 0, v[226:227]
	v_lshl_add_u64 v[222:223], v[222:223], 0, v[228:229]
	v_lshl_add_u64 v[224:225], v[224:225], 0, v[228:229]
	global_load_dword v251, v[220:221], off
	global_load_ushort v236, v[222:223], off
	global_load_ushort v237, v[224:225], off
	v_lshl_add_u64 v[220:221], v[220:221], 0, v[226:227]
	v_lshl_add_u64 v[222:223], v[222:223], 0, v[228:229]
	v_lshl_add_u64 v[224:225], v[224:225], 0, v[228:229]
	global_load_dword v238, v[220:221], off
	global_load_ushort v239, v[222:223], off
	global_load_ushort v240, v[224:225], off
	v_lshl_add_u64 v[220:221], v[220:221], 0, v[226:227]
	v_lshl_add_u64 v[222:223], v[222:223], 0, v[228:229]
	v_lshl_add_u64 v[224:225], v[224:225], 0, v[228:229]
	global_load_dword v241, v[220:221], off
	global_load_ushort v242, v[222:223], off
	global_load_ushort v243, v[224:225], off
	v_lshl_add_u64 v[220:221], v[220:221], 0, v[226:227]
	v_lshl_add_u64 v[222:223], v[222:223], 0, v[228:229]
	v_lshl_add_u64 v[224:225], v[224:225], 0, v[228:229]
	global_load_dword v244, v[220:221], off
	global_load_ushort v245, v[222:223], off
	global_load_ushort v246, v[224:225], off
	v_lshl_add_u64 v[220:221], v[220:221], 0, v[226:227]
	v_lshl_add_u64 v[222:223], v[222:223], 0, v[228:229]
	v_lshl_add_u64 v[224:225], v[224:225], 0, v[228:229]
	global_load_dword v247, v[220:221], off
	global_load_ushort v248, v[222:223], off
	global_load_ushort v249, v[224:225], off
	v_lshl_add_u64 v[220:221], v[220:221], 0, v[226:227]
	v_lshl_add_u64 v[222:223], v[222:223], 0, v[228:229]
	v_lshl_add_u64 v[224:225], v[224:225], 0, v[228:229]
	global_load_dword v250, v[220:221], off
	global_load_ushort v251, v[222:223], off
	global_load_ushort v236, v[224:225], off
	v_lshl_add_u64 v[220:221], v[220:221], 0, v[226:227]
	v_lshl_add_u64 v[222:223], v[222:223], 0, v[228:229]
	v_lshl_add_u64 v[224:225], v[224:225], 0, v[228:229]
	global_load_dword v237, v[220:221], off
	global_load_ushort v238, v[222:223], off
	global_load_ushort v239, v[224:225], off
	v_lshl_add_u64 v[220:221], v[220:221], 0, v[226:227]
	v_lshl_add_u64 v[222:223], v[222:223], 0, v[228:229]
	v_lshl_add_u64 v[224:225], v[224:225], 0, v[228:229]
	global_load_dword v240, v[220:221], off
	global_load_ushort v241, v[222:223], off
	global_load_ushort v242, v[224:225], off
	v_lshl_add_u64 v[220:221], v[220:221], 0, v[226:227]
	v_lshl_add_u64 v[222:223], v[222:223], 0, v[228:229]
	v_lshl_add_u64 v[224:225], v[224:225], 0, v[228:229]
	global_load_dword v243, v[220:221], off
	global_load_ushort v244, v[222:223], off
	global_load_ushort v245, v[224:225], off
	v_lshl_add_u64 v[220:221], v[220:221], 0, v[226:227]
	v_lshl_add_u64 v[222:223], v[222:223], 0, v[228:229]
	v_lshl_add_u64 v[224:225], v[224:225], 0, v[228:229]
	global_load_dword v246, v[220:221], off
	global_load_ushort v247, v[222:223], off
	global_load_ushort v248, v[224:225], off
	v_lshl_add_u64 v[220:221], v[220:221], 0, v[226:227]
	v_lshl_add_u64 v[222:223], v[222:223], 0, v[228:229]
	v_lshl_add_u64 v[224:225], v[224:225], 0, v[228:229]
	global_load_dword v249, v[220:221], off
	global_load_ushort v250, v[222:223], off
	global_load_ushort v251, v[224:225], off
	global_load_dword v44, v[38:39], off
	v_lshl_add_u64 v[38:39], v[36:37], 2, s[36:37]
	v_lshlrev_b64 v[34:35], 1, v[34:35]
	global_load_dword v45, v[38:39], off
	v_lshl_add_u64 v[38:39], s[28:29], 0, v[34:35]
	v_lshlrev_b64 v[36:37], 1, v[36:37]
	global_load_ushort v40, v[38:39], off
	v_lshl_add_u64 v[38:39], s[28:29], 0, v[36:37]
	global_load_ushort v38, v[38:39], off
	v_lshl_add_u64 v[34:35], s[0:1], 0, v[34:35]
	v_or_b32_e32 v80, 2, v32
	s_movk_i32 s25, 0x50
	v_lshlrev_b32_e32 v136, 3, v81
	v_cmp_eq_u32_e64 s[38:39], 0, v81
	s_mov_b32 s31, 0
	v_xad_u32 v148, v133, -1, s27
	v_writelane_b32 v232, s21, 58
	s_waitcnt vmcnt(0)
	v_lshl_or_b32 v113, v38, 16, v40
	global_load_ushort v38, v[34:35], off
	v_lshl_add_u64 v[34:35], s[0:1], 0, v[36:37]
	global_load_ushort v34, v[34:35], off
	v_xad_u32 v35, v32, -3, s27
	v_cndmask_b32_e32 v35, v35, v80, vcc
	v_add_u32_e32 v36, s97, v35
	v_ashrrev_i32_e32 v37, 31, v36
	v_mul_u32_u24_e32 v80, 0x88, v80
	v_add_lshl_u32 v141, v42, v80, 1
	v_add_u32_e32 v142, 0x220, v141
	v_add_u32_e32 v143, 0x440, v141
	v_add_u32_e32 v144, 0x660, v141
	v_add_u32_e32 v145, 0x880, v141
	v_add_u32_e32 v146, 0xaa0, v141
	v_add_u32_e32 v147, 0xcc0, v141
	s_waitcnt vmcnt(0)
	v_lshl_or_b32 v34, v34, 16, v38
	v_add_u32_e32 v38, s24, v36
	v_lshlrev_b64 v[36:37], 9, v[36:37]
	v_ashrrev_i32_e32 v39, 31, v38
	v_lshl_add_u64 v[36:37], v[36:37], 0, v[42:43]
	v_lshlrev_b64 v[38:39], 9, v[38:39]
	v_lshl_add_u64 v[40:41], v[36:37], 2, s[36:37]
	v_lshl_add_u64 v[38:39], v[38:39], 0, v[42:43]
	global_load_dword v46, v[40:41], off
	v_lshl_add_u64 v[40:41], v[38:39], 2, s[36:37]
	v_lshlrev_b64 v[36:37], 1, v[36:37]
	global_load_dword v47, v[40:41], off
	v_lshl_add_u64 v[40:41], s[28:29], 0, v[36:37]
	v_lshlrev_b64 v[38:39], 1, v[38:39]
	global_load_ushort v35, v[40:41], off
	v_lshl_add_u64 v[40:41], s[28:29], 0, v[38:39]
	global_load_ushort v40, v[40:41], off
	v_lshl_add_u64 v[36:37], s[0:1], 0, v[36:37]
	s_waitcnt vmcnt(0)
	v_lshl_or_b32 v115, v40, 16, v35
	global_load_ushort v35, v[36:37], off
	v_lshl_add_u64 v[36:37], s[0:1], 0, v[38:39]
	global_load_ushort v36, v[36:37], off
	v_xad_u32 v37, v32, -5, s27
	s_waitcnt vmcnt(0)
	v_lshl_or_b32 v35, v36, 16, v35
	v_or_b32_e32 v36, 4, v32
	v_cndmask_b32_e32 v36, v37, v36, vcc
	v_add_u32_e32 v36, s97, v36
	v_add_u32_e32 v38, s24, v36
	v_ashrrev_i32_e32 v37, 31, v36
	v_lshlrev_b64 v[36:37], 9, v[36:37]
	v_ashrrev_i32_e32 v39, 31, v38
	v_lshl_add_u64 v[36:37], v[36:37], 0, v[42:43]
	v_lshlrev_b64 v[38:39], 9, v[38:39]
	v_lshl_add_u64 v[40:41], v[36:37], 2, s[36:37]
	v_lshl_add_u64 v[38:39], v[38:39], 0, v[42:43]
	global_load_dword v118, v[40:41], off
	v_lshl_add_u64 v[40:41], v[38:39], 2, s[36:37]
	v_lshlrev_b64 v[36:37], 1, v[36:37]
	global_load_dword v119, v[40:41], off
	v_lshl_add_u64 v[40:41], s[28:29], 0, v[36:37]
	v_lshlrev_b64 v[38:39], 1, v[38:39]
	global_load_ushort v82, v[40:41], off
	v_lshl_add_u64 v[40:41], s[28:29], 0, v[38:39]
	global_load_ushort v40, v[40:41], off
	v_lshl_add_u64 v[36:37], s[0:1], 0, v[36:37]
	s_waitcnt vmcnt(0)
	v_lshl_or_b32 v134, v40, 16, v82
	global_load_ushort v40, v[36:37], off
	v_lshl_add_u64 v[36:37], s[0:1], 0, v[38:39]
	global_load_ushort v36, v[36:37], off
	v_or_b32_e32 v37, 6, v32
	v_xad_u32 v38, v32, -7, s27
	v_cndmask_b32_e32 v37, v38, v37, vcc
	v_add_u32_e32 v38, s97, v37
	v_ashrrev_i32_e32 v39, 31, v38
	s_waitcnt vmcnt(0)
	v_lshl_or_b32 v36, v36, 16, v40
	v_add_u32_e32 v40, s24, v38
	v_lshlrev_b64 v[38:39], 9, v[38:39]
	v_ashrrev_i32_e32 v41, 31, v40
	v_lshl_add_u64 v[38:39], v[38:39], 0, v[42:43]
	v_lshlrev_b64 v[40:41], 9, v[40:41]
	v_lshl_add_u64 v[82:83], v[38:39], 2, s[36:37]
	v_lshl_add_u64 v[40:41], v[40:41], 0, v[42:43]
	global_load_dword v120, v[82:83], off
	v_lshl_add_u64 v[82:83], v[40:41], 2, s[36:37]
	v_lshlrev_b64 v[38:39], 1, v[38:39]
	global_load_dword v121, v[82:83], off
	v_lshl_add_u64 v[82:83], s[28:29], 0, v[38:39]
	v_lshlrev_b64 v[40:41], 1, v[40:41]
	global_load_ushort v37, v[82:83], off
	v_lshl_add_u64 v[82:83], s[28:29], 0, v[40:41]
	global_load_ushort v82, v[82:83], off
	v_lshl_add_u64 v[38:39], s[0:1], 0, v[38:39]
	s_waitcnt vmcnt(0)
	v_lshl_or_b32 v140, v82, 16, v37
	global_load_ushort v37, v[38:39], off
	v_lshl_add_u64 v[38:39], s[0:1], 0, v[40:41]
	global_load_ushort v38, v[38:39], off
	v_xad_u32 v39, v32, -9, s27
	s_waitcnt vmcnt(0)
	v_lshl_or_b32 v37, v38, 16, v37
	v_or_b32_e32 v38, 8, v32
	v_cndmask_b32_e32 v38, v39, v38, vcc
	v_add_u32_e32 v38, s97, v38
	v_add_u32_e32 v40, s24, v38
	v_ashrrev_i32_e32 v39, 31, v38
	v_lshlrev_b64 v[38:39], 9, v[38:39]
	v_ashrrev_i32_e32 v41, 31, v40
	v_lshl_add_u64 v[38:39], v[38:39], 0, v[42:43]
	v_lshlrev_b64 v[40:41], 9, v[40:41]
	v_lshl_add_u64 v[82:83], v[38:39], 2, s[36:37]
	v_lshl_add_u64 v[40:41], v[40:41], 0, v[42:43]
	global_load_dword v122, v[82:83], off
	v_lshl_add_u64 v[82:83], v[40:41], 2, s[36:37]
	v_lshlrev_b64 v[38:39], 1, v[38:39]
	global_load_dword v123, v[82:83], off
	v_lshl_add_u64 v[82:83], s[28:29], 0, v[38:39]
	v_lshlrev_b64 v[40:41], 1, v[40:41]
	global_load_ushort v84, v[82:83], off
	v_lshl_add_u64 v[82:83], s[28:29], 0, v[40:41]
	global_load_ushort v82, v[82:83], off
	v_lshl_add_u64 v[38:39], s[0:1], 0, v[38:39]
	s_waitcnt vmcnt(0)
	v_lshl_or_b32 v152, v82, 16, v84
	global_load_ushort v82, v[38:39], off
	v_lshl_add_u64 v[38:39], s[0:1], 0, v[40:41]
	global_load_ushort v38, v[38:39], off
	v_or_b32_e32 v39, 10, v32
	v_xad_u32 v40, v32, -11, s27
	v_cndmask_b32_e32 v39, v40, v39, vcc
	v_add_u32_e32 v40, s97, v39
	v_ashrrev_i32_e32 v41, 31, v40
	s_waitcnt vmcnt(0)
	v_lshl_or_b32 v38, v38, 16, v82
	v_add_u32_e32 v82, s24, v40
	v_lshlrev_b64 v[40:41], 9, v[40:41]
	v_ashrrev_i32_e32 v83, 31, v82
	v_lshl_add_u64 v[40:41], v[40:41], 0, v[42:43]
	v_lshlrev_b64 v[82:83], 9, v[82:83]
	v_lshl_add_u64 v[84:85], v[40:41], 2, s[36:37]
	v_lshl_add_u64 v[82:83], v[82:83], 0, v[42:43]
	global_load_dword v124, v[84:85], off
	v_lshl_add_u64 v[84:85], v[82:83], 2, s[36:37]
	v_lshlrev_b64 v[40:41], 1, v[40:41]
	global_load_dword v125, v[84:85], off
	v_lshl_add_u64 v[84:85], s[28:29], 0, v[40:41]
	v_lshlrev_b64 v[82:83], 1, v[82:83]
	global_load_ushort v39, v[84:85], off
	v_lshl_add_u64 v[84:85], s[28:29], 0, v[82:83]
	global_load_ushort v84, v[84:85], off
	v_lshl_add_u64 v[40:41], s[0:1], 0, v[40:41]
	s_waitcnt vmcnt(0)
	v_lshl_or_b32 v153, v84, 16, v39
	global_load_ushort v39, v[40:41], off
	v_lshl_add_u64 v[40:41], s[0:1], 0, v[82:83]
	global_load_ushort v40, v[40:41], off
	v_xad_u32 v41, v32, -13, s27
	s_waitcnt vmcnt(0)
	v_lshl_or_b32 v39, v40, 16, v39
	v_or_b32_e32 v40, 12, v32
	v_cndmask_b32_e32 v40, v41, v40, vcc
	v_add_u32_e32 v40, s97, v40
	v_add_u32_e32 v82, s24, v40
	v_ashrrev_i32_e32 v41, 31, v40
	v_lshlrev_b64 v[40:41], 9, v[40:41]
	v_ashrrev_i32_e32 v83, 31, v82
	v_lshl_add_u64 v[40:41], v[40:41], 0, v[42:43]
	v_lshlrev_b64 v[82:83], 9, v[82:83]
	v_lshl_add_u64 v[84:85], v[40:41], 2, s[36:37]
	v_lshl_add_u64 v[82:83], v[82:83], 0, v[42:43]
	global_load_dword v128, v[84:85], off
	v_lshl_add_u64 v[84:85], v[82:83], 2, s[36:37]
	v_lshlrev_b64 v[40:41], 1, v[40:41]
	global_load_dword v129, v[84:85], off
	v_lshl_add_u64 v[84:85], s[28:29], 0, v[40:41]
	v_lshlrev_b64 v[82:83], 1, v[82:83]
	global_load_ushort v86, v[84:85], off
	v_lshl_add_u64 v[84:85], s[28:29], 0, v[82:83]
	global_load_ushort v84, v[84:85], off
	v_lshl_add_u64 v[40:41], s[0:1], 0, v[40:41]
	s_waitcnt vmcnt(0)
	v_lshl_or_b32 v154, v84, 16, v86
	global_load_ushort v84, v[40:41], off
	v_lshl_add_u64 v[40:41], s[0:1], 0, v[82:83]
	global_load_ushort v40, v[40:41], off
	v_or_b32_e32 v41, 14, v32
	v_xad_u32 v82, v32, -15, s27
	v_cndmask_b32_e32 v41, v82, v41, vcc
	v_add_u32_e32 v82, s97, v41
	v_ashrrev_i32_e32 v83, 31, v82
	s_waitcnt vmcnt(0)
	v_lshl_or_b32 v40, v40, 16, v84
	v_add_u32_e32 v84, s24, v82
	v_lshlrev_b64 v[82:83], 9, v[82:83]
	v_ashrrev_i32_e32 v85, 31, v84
	v_lshl_add_u64 v[82:83], v[82:83], 0, v[42:43]
	v_lshlrev_b64 v[84:85], 9, v[84:85]
	v_lshl_add_u64 v[86:87], v[82:83], 2, s[36:37]
	v_lshl_add_u64 v[84:85], v[84:85], 0, v[42:43]
	global_load_dword v130, v[86:87], off
	v_lshl_add_u64 v[86:87], v[84:85], 2, s[36:37]
	v_lshlrev_b64 v[82:83], 1, v[82:83]
	global_load_dword v131, v[86:87], off
	v_lshl_add_u64 v[86:87], s[28:29], 0, v[82:83]
	v_lshlrev_b64 v[84:85], 1, v[84:85]
	global_load_ushort v41, v[86:87], off
	v_lshl_add_u64 v[86:87], s[28:29], 0, v[84:85]
	global_load_ushort v86, v[86:87], off
	v_lshl_add_u64 v[82:83], s[0:1], 0, v[82:83]
	s_waitcnt vmcnt(0)
	v_lshl_or_b32 v155, v86, 16, v41
	global_load_ushort v41, v[82:83], off
	v_lshl_add_u64 v[82:83], s[0:1], 0, v[84:85]
	global_load_ushort v82, v[82:83], off
	v_lshlrev_b32_e32 v85, 2, v81
	v_or_b32_e32 v80, 2, v85
	v_cmp_gt_u32_e64 s[44:45], v80, v133
	v_or_b32_e32 v80, 3, v85
	v_cmp_gt_u32_e64 s[46:47], v80, v133
	v_or_b32_e32 v80, 8, v85
	v_cmp_gt_u32_e64 s[48:49], v80, v133
	v_or_b32_e32 v80, 9, v85
	v_cmp_gt_u32_e64 s[50:51], v80, v133
	v_or_b32_e32 v80, 10, v85
	v_cmp_gt_u32_e64 s[52:53], v80, v133
	v_or_b32_e32 v80, 11, v85
	v_cmp_gt_u32_e64 s[54:55], v80, v133
	v_or_b32_e32 v80, 16, v85
	v_cmp_gt_u32_e64 s[56:57], v80, v133
	v_or_b32_e32 v80, 17, v85
	v_cmp_gt_u32_e64 s[58:59], v80, v133
	v_or_b32_e32 v80, 18, v85
	v_cmp_gt_u32_e64 s[60:61], v80, v133
	v_or_b32_e32 v80, 19, v85
	v_cmp_gt_u32_e64 s[62:63], v80, v133
	v_or_b32_e32 v80, 24, v85
	v_mul_lo_u32 v84, v42, s25
	v_cmp_gt_u32_e64 s[64:65], v80, v133
	v_or_b32_e32 v80, 25, v85
	v_lshl_add_u32 v135, v81, 5, v84
	s_movk_i32 s25, 0xffe8
	v_cmp_gt_u32_e64 s[66:67], v80, v133
	v_or_b32_e32 v80, 26, v85
	v_mad_i32_i24 v138, v81, s25, v135
	s_movk_i32 s25, 0xffb4
	v_mul_u32_u24_e32 v81, 0x880, v81
	v_cmp_gt_u32_e64 s[68:69], v80, v133
	v_or_b32_e32 v80, 27, v85
	v_add_lshl_u32 v139, v42, v81, 1
	v_cmp_gt_u32_e64 s[70:71], v80, v133
	v_mul_u32_u24_e32 v80, 0x50, v133
	v_sub_u32_e32 v81, s27, v32
	v_cmp_lt_u32_e64 s[42:43], v85, v133
	v_subrev_u32_e32 v149, 33, v81
	v_add_u32_e32 v151, v32, v80
	s_waitcnt vmcnt(0)
	v_lshl_or_b32 v41, v82, 16, v41
	v_mul_u32_u24_e32 v82, 0x110, v133
	v_or_b32_e32 v137, v82, v136
	v_lshl_add_u64 v[82:83], v[116:117], 2, s[40:41]
	v_lshl_add_u64 v[126:127], v[82:83], 0, v[32:33]
	v_mul_lo_u32 v82, v42, s25
	v_cmp_gt_u32_e64 s[40:41], v85, v133
	v_add_u32_e32 v150, v84, v82
	s_mov_b32 s25, 0
	s_branch .LBB0_785

.LBB0_787:
	s_or_b64 exec, exec, s[74:75]
	s_add_i32 s25, s25, 1
	v_readlane_b32 s74, v232, 17
	v_readlane_b32 s76, v232, 19
	s_cmp_ge_u32 s25, s30
	v_readlane_b32 s75, v232, 18
	v_readlane_b32 s77, v232, 20
	s_cbranch_scc1 .LBB0_784
	v_add_u32_e32 v230, s31, v32
	v_mov_b32_e32 v226, s24
	v_add_u32_e32 v230, 32, v230
	v_lshlrev_b32_e32 v226, 11, v226
	v_cndmask_b32_e32 v220, v149, v230, vcc
	v_ashrrev_i32_e32 v227, 31, v226
	v_add_u32_e32 v220, s97, v220
	v_ashrrev_i32_e32 v228, 1, v226
	v_ashrrev_i32_e32 v221, 31, v220
	v_mov_b32_e32 v229, v227
	v_lshlrev_b64 v[220:221], 9, v[220:221]
	v_lshl_add_u64 v[220:221], v[220:221], 0, v[42:43]
	v_lshl_add_u64 v[222:223], v[220:221], 1, s[28:29]
	v_lshl_add_u64 v[224:225], v[220:221], 1, s[0:1]
	v_lshl_add_u64 v[220:221], v[220:221], 2, s[36:37]
	global_load_dword v44, v[220:221], off
	global_load_ushort v113, v[222:223], off
	global_load_ushort v34, v[224:225], off
	v_lshl_add_u64 v[220:221], v[220:221], 0, v[226:227]
	v_lshl_add_u64 v[222:223], v[222:223], 0, v[228:229]
	v_lshl_add_u64 v[224:225], v[224:225], 0, v[228:229]
	global_load_dword v45, v[220:221], off
	global_load_ushort v236, v[222:223], off
	global_load_ushort v237, v[224:225], off
	v_lshl_add_u64 v[220:221], v[220:221], 0, v[226:227]
	v_lshl_add_u64 v[222:223], v[222:223], 0, v[228:229]
	v_lshl_add_u64 v[224:225], v[224:225], 0, v[228:229]
	global_load_dword v46, v[220:221], off
	global_load_ushort v115, v[222:223], off
	global_load_ushort v35, v[224:225], off
	v_lshl_add_u64 v[220:221], v[220:221], 0, v[226:227]
	v_lshl_add_u64 v[222:223], v[222:223], 0, v[228:229]
	v_lshl_add_u64 v[224:225], v[224:225], 0, v[228:229]
	global_load_dword v47, v[220:221], off
	global_load_ushort v238, v[222:223], off
	global_load_ushort v239, v[224:225], off
	v_lshl_add_u64 v[220:221], v[220:221], 0, v[226:227]
	v_lshl_add_u64 v[222:223], v[222:223], 0, v[228:229]
	v_lshl_add_u64 v[224:225], v[224:225], 0, v[228:229]
	global_load_dword v118, v[220:221], off
	global_load_ushort v134, v[222:223], off
	global_load_ushort v36, v[224:225], off
	v_lshl_add_u64 v[220:221], v[220:221], 0, v[226:227]
	v_lshl_add_u64 v[222:223], v[222:223], 0, v[228:229]
	v_lshl_add_u64 v[224:225], v[224:225], 0, v[228:229]
	global_load_dword v119, v[220:221], off
	global_load_ushort v240, v[222:223], off
	global_load_ushort v241, v[224:225], off
	v_lshl_add_u64 v[220:221], v[220:221], 0, v[226:227]
	v_lshl_add_u64 v[222:223], v[222:223], 0, v[228:229]
	v_lshl_add_u64 v[224:225], v[224:225], 0, v[228:229]
	global_load_dword v120, v[220:221], off
	global_load_ushort v140, v[222:223], off
	global_load_ushort v37, v[224:225], off
	v_lshl_add_u64 v[220:221], v[220:221], 0, v[226:227]
	v_lshl_add_u64 v[222:223], v[222:223], 0, v[228:229]
	v_lshl_add_u64 v[224:225], v[224:225], 0, v[228:229]
	global_load_dword v121, v[220:221], off
	global_load_ushort v242, v[222:223], off
	global_load_ushort v243, v[224:225], off
	v_lshl_add_u64 v[220:221], v[220:221], 0, v[226:227]
	v_lshl_add_u64 v[222:223], v[222:223], 0, v[228:229]
	v_lshl_add_u64 v[224:225], v[224:225], 0, v[228:229]
	global_load_dword v122, v[220:221], off
	global_load_ushort v152, v[222:223], off
	global_load_ushort v38, v[224:225], off
	v_lshl_add_u64 v[220:221], v[220:221], 0, v[226:227]
	v_lshl_add_u64 v[222:223], v[222:223], 0, v[228:229]
	v_lshl_add_u64 v[224:225], v[224:225], 0, v[228:229]
	global_load_dword v123, v[220:221], off
	global_load_ushort v245, v[222:223], off
	global_load_ushort v244, v[224:225], off
	v_lshl_add_u64 v[220:221], v[220:221], 0, v[226:227]
	v_lshl_add_u64 v[222:223], v[222:223], 0, v[228:229]
	v_lshl_add_u64 v[224:225], v[224:225], 0, v[228:229]
	global_load_dword v124, v[220:221], off
	global_load_ushort v153, v[222:223], off
	global_load_ushort v39, v[224:225], off
	v_lshl_add_u64 v[220:221], v[220:221], 0, v[226:227]
	v_lshl_add_u64 v[222:223], v[222:223], 0, v[228:229]
	v_lshl_add_u64 v[224:225], v[224:225], 0, v[228:229]
	global_load_dword v125, v[220:221], off
	global_load_ushort v247, v[222:223], off
	global_load_ushort v246, v[224:225], off
	v_lshl_add_u64 v[220:221], v[220:221], 0, v[226:227]
	v_lshl_add_u64 v[222:223], v[222:223], 0, v[228:229]
	v_lshl_add_u64 v[224:225], v[224:225], 0, v[228:229]
	global_load_dword v128, v[220:221], off
	global_load_ushort v154, v[222:223], off
	global_load_ushort v40, v[224:225], off
	v_lshl_add_u64 v[220:221], v[220:221], 0, v[226:227]
	v_lshl_add_u64 v[222:223], v[222:223], 0, v[228:229]
	v_lshl_add_u64 v[224:225], v[224:225], 0, v[228:229]
	global_load_dword v129, v[220:221], off
	global_load_ushort v249, v[222:223], off
	global_load_ushort v248, v[224:225], off
	v_lshl_add_u64 v[220:221], v[220:221], 0, v[226:227]
	v_lshl_add_u64 v[222:223], v[222:223], 0, v[228:229]
	v_lshl_add_u64 v[224:225], v[224:225], 0, v[228:229]
	global_load_dword v130, v[220:221], off
	global_load_ushort v155, v[222:223], off
	global_load_ushort v41, v[224:225], off
	v_lshl_add_u64 v[220:221], v[220:221], 0, v[226:227]
	v_lshl_add_u64 v[222:223], v[222:223], 0, v[228:229]
	v_lshl_add_u64 v[224:225], v[224:225], 0, v[228:229]
	global_load_dword v131, v[220:221], off
	global_load_ushort v250, v[222:223], off
	global_load_ushort v251, v[224:225], off
	s_branch .LBB0_784
